# strategy 1: counted vmcnt(8) at the GLA scan loop top so the 8 output stores of the previous chunk stay in flight (vmcnt(0) once before the loop), on top of v9
# speedup vs baseline: 1.0063x; 1.0063x over previous
; __device__ __forceinline__ void gla_scan_item(Frame& F, const int sitem) {
;     ...
;     const int tid = F.tid, lane = F.lane, r = lane & 31, h = lane >> 5, w = F.wave, dvs = w & 1, dkq = w >> 1;
;     const unsigned oq = (unsigned)((tid >> 5) * 1024 + 8 * (tid & 31)), o8 = (unsigned)(8 * tid), od = (unsigned)(4 * tid);
;     v4u rq[4], rk[4], ra, rv, rd = (v4u){0u, 0u, 0u, 0u};
;     ...
;     f32x16 S[2];
; #pragma unroll
;     for (int kt = 0; kt < 2; ++kt)
; #pragma unroll
;         for (int i = 0; i < 16; ++i) S[kt][i] = 0.f;
;     GLA_LOAD(0);
;     const ldsp wq = Qs + (tid >> 5) * QP + (tid & 31) * 16, wk = Kt + (tid >> 3) * TP + (tid & 7) * 16, wa = As + (tid >> 3) * TP + (tid & 7) * 16, wv = Vs + (tid >> 3) * TP + (tid & 7) * 16;
;     const int dk0 = 64 * dkq;
; #pragma unroll 1
.LBB0_709:
	s_or_b64 exec, exec, s[18:19]
	v_lshrrev_b32_e32 v8, 5, v162
	s_bfe_u32 s50, s55, 0x10006
	s_ashr_i32 s8, s55, 7
	s_lshl_b64 s[18:19], s[48:49], 12
	s_movk_i32 s9, 0x210
	v_lshrrev_b32_e32 v10, 3, v163
	v_readlane_b32 s10, v255, 10
	v_lshl_add_u64 v[98:99], s[46:47], 0, v[2:3]
	v_lshl_add_u64 v[144:145], s[52:53], 0, v[2:3]
	v_lshl_add_u64 v[146:147], s[4:5], 0, v[2:3]
	v_lshlrev_b32_e32 v2, 3, v8
	s_and_b32 s4, s55, 0xffffff80
	v_mul_lo_u32 v7, v7, s9
	v_mul_lo_u32 v10, v10, s75
	v_readlane_b32 s9, v255, 9
	v_lshl_add_u64 v[148:149], v[4:5], 2, s[44:45]
	v_add_u32_e32 v3, 0, v2
	v_lshl_or_b32 v4, s50, 5, v6
	v_mov_b32_e32 v5, s10
	v_lshlrev_b32_e32 v154, 4, v8
	s_cmp_gt_u32 s54, 1
	v_readlane_b32 s11, v255, 11
	v_add_u32_e32 v11, 0, v10
	v_add_u32_e32 v13, s9, v10
	v_add_u32_e32 v10, s10, v10
	v_add_u32_e32 v14, s4, v3
	v_mad_u32_u24 v15, v4, s75, v5
	s_cselect_b64 s[4:5], -1, 0
	v_mov_b32_e32 v4, s9
	s_lshl_b32 s9, s54, 13
	s_add_i32 s10, 0, 0x16000
	s_waitcnt lgkmcnt(0)
	v_add_u32_e32 v16, s11, v154
	s_ashr_i32 s11, s55, 8
	s_lshl_b32 s47, s50, 13
	s_add_i32 s9, s10, s9
	s_lshl_b32 s44, s11, 5
	s_add_i32 s10, s10, s47
	s_lshl_b32 s11, s11, 12
	v_lshlrev_b32_e32 v156, 4, v162
	s_and_b32 s46, s54, 2
	s_add_i32 s10, s10, s11
	v_add_u32_e32 v157, s10, v156
	s_lshl_b32 s10, s46, 10
	s_ashr_i32 s45, s44, 31
	s_lshl_b32 s47, s8, 8
	s_or_b32 s11, s10, 0x400
	s_bfe_u32 s46, s54, 0x10001
	v_mad_u32_u24 v155, v6, s75, v4
	v_lshl_or_b32 v4, s8, 6, v6
	s_add_u32 s18, s44, s18
	v_mul_lo_u32 v19, v4, s75
	s_addc_u32 s44, s45, s19
	v_lshl_or_b32 v4, v8, 2, s18
	s_lshl_b32 s48, s50, 6
	s_lshl_b64 s[18:19], s[0:1], 1
	s_add_u32 s18, s18, s48
	s_mul_i32 s45, s12, 0x300
	s_addc_u32 s19, s19, 0
	s_add_u32 s18, s18, s45
	s_mul_i32 s46, s46, 0xc000
	s_addc_u32 s19, s19, 0
	s_add_u32 s18, s18, s46
	s_addc_u32 s19, s19, 0
	v_add_u32_e32 v17, v3, v2
	v_mov_b64_e32 v[2:3], s[18:19]
	s_movk_i32 s18, 0xc00
	s_add_u32 s14, s14, s26
	v_lshlrev_b32_e32 v97, 4, v163
	v_mad_u64_u32 v[2:3], s[18:19], v4, s18, v[2:3]
	s_addc_u32 s15, s15, 0
	v_add_u32_e32 v7, 0, v7
	v_lshlrev_b32_e32 v9, 4, v6
	v_and_b32_e32 v12, 0x70, v97
	v_mul_u32_u24_e32 v18, 0x210, v6
	v_mad_i32_i24 v3, s44, v245, v3
	v_lshlrev_b32_e32 v4, 1, v6
	v_mov_b32_e32 v5, v96
	v_lshl_add_u64 v[152:153], v[0:1], 1, s[14:15]
	s_add_i32 s26, s13, s12
	v_mov_b32_e32 v0, 0
	v_lshl_add_u64 v[150:151], v[2:3], 0, v[4:5]
	s_add_i32 s26, s26, 4
	s_mov_b32 s44, 0
	v_add_u32_e32 v158, v7, v9
	v_add_u32_e32 v159, v11, v12
	v_add_u32_e32 v160, v13, v12
	v_add_u32_e32 v161, v10, v12
	v_add_u32_e32 v162, v14, v18
	v_add_u32_e32 v163, v15, v154
	v_add_u32_e32 v164, s47, v16
	v_add_u32_e32 v165, v17, v19
	v_mov_b32_e32 v1, v0
	v_mov_b32_e32 v2, v0
	v_mov_b32_e32 v3, v0
	v_mov_b32_e32 v4, v0
	v_mov_b32_e32 v5, v0
	v_mov_b32_e32 v6, v0
	v_mov_b32_e32 v7, v0
	v_mov_b32_e32 v8, v0
	v_mov_b32_e32 v9, v0
	v_mov_b32_e32 v10, v0
	v_mov_b32_e32 v11, v0
	v_mov_b32_e32 v12, v0
	v_mov_b32_e32 v13, v0
	v_mov_b32_e32 v14, v0
	v_mov_b32_e32 v15, v0
	v_mov_b32_e32 v16, v0
	v_mov_b32_e32 v17, v0
	v_mov_b32_e32 v18, v0
	v_mov_b32_e32 v19, v0
	v_mov_b32_e32 v20, v0
	v_mov_b32_e32 v21, v0
	v_mov_b32_e32 v22, v0
	v_mov_b32_e32 v23, v0
	v_mov_b32_e32 v24, v0
	v_mov_b32_e32 v25, v0
	v_mov_b32_e32 v26, v0
	v_mov_b32_e32 v27, v0
	v_mov_b32_e32 v28, v0
	v_mov_b32_e32 v29, v0
	v_mov_b32_e32 v30, v0
	v_mov_b32_e32 v31, v0
	s_waitcnt vmcnt(0)
	s_branch .LBB0_711

; #define LAS __attribute__((address_space(3)))
; #define BAR_L() do { asm volatile("s_waitcnt lgkmcnt(0)" ::: "memory"); __builtin_amdgcn_s_barrier(); asm volatile("" ::: "memory"); } while (0)
; __device__ __forceinline__ void gla_scan_item(Frame& F, const int sitem) {
;     ...
;     for (int n = 0; n < 64; ++n) {
; #pragma unroll
;         for (int q = 0; q < 4; ++q) *(LAS v4u*)(wq + q * 16 * QP) = rq[q];
; #pragma unroll
;         for (int q = 0; q < 4; ++q) *(LAS v4u*)(wk + q * 64 * TP) = rk[q];
;         *(LAS v4u*)(wa) = ra; *(LAS v4u*)(wv) = rv;
;         if (tid < 64) *(LAS v4u*)(Dc + tid * 16) = rd;
;         BAR_L();
;         if (n + 1 < 64) GLA_LOAD(n + 1);
.LBB0_711:
	s_waitcnt vmcnt(8)
	ds_write_b128 v158, v[80:83]
	ds_write_b128 v158, v[84:87] offset:8448
	ds_write_b128 v158, v[88:91] offset:16896
	ds_write_b128 v158, v[92:95] offset:25344
	ds_write_b128 v159, v[100:103] offset:33792
	ds_write_b128 v159, v[104:107] offset:43008
	ds_write_b128 v159, v[112:115] offset:52224
	ds_write_b128 v159, v[116:119] offset:61440
	ds_write_b128 v160, v[120:123]
	ds_write_b128 v161, v[124:127]
	s_and_saveexec_b64 s[14:15], s[40:41]
	v_add_u32_e32 v32, 0, v97
	v_add_u32_e32 v32, 0x15c00, v32
	ds_write_b128 v32, v[108:111]
	s_or_b64 exec, exec, s[14:15]
	s_waitcnt lgkmcnt(0)
	s_barrier
	s_cmpk_eq_i32 s44, 0xfc
	s_cbranch_scc1 .LBB0_717
	v_lshl_add_u64 v[32:33], s[42:43], 0, v[152:153]
	v_add_co_u32_e32 v34, vcc, 0x34020000, v32
	s_add_i32 s14, s26, s44
	s_nop 0
	v_addc_co_u32_e32 v35, vcc, 0, v33, vcc
	v_add_co_u32_e32 v36, vcc, 0x34028000, v32
	s_ashr_i32 s15, s14, 31
	s_nop 0
	v_addc_co_u32_e32 v37, vcc, 0, v33, vcc
	flat_load_dwordx4 v[80:83], v[34:35]
	flat_load_dwordx4 v[84:87], v[36:37]
	v_add_co_u32_e32 v34, vcc, 0x34030000, v32
	s_lshl_b64 s[12:13], s[14:15], 15
	s_nop 0
	v_addc_co_u32_e32 v35, vcc, 0, v33, vcc
	v_add_co_u32_e32 v32, vcc, 0x34038000, v32
	s_mul_i32 s18, s14, 0x180
	s_nop 0
	v_addc_co_u32_e32 v33, vcc, 0, v33, vcc
	flat_load_dwordx4 v[88:91], v[34:35]
	flat_load_dwordx4 v[92:95], v[32:33]
	v_lshl_add_u64 v[32:33], v[98:99], 0, s[12:13]
	v_add_co_u32_e32 v34, vcc, s3, v32
	s_mul_hi_i32 s19, s14, 0x180
	s_nop 0
	v_addc_co_u32_e32 v35, vcc, 0, v33, vcc
	flat_load_dwordx4 v[100:103], v[32:33]
	flat_load_dwordx4 v[104:107], v[34:35]
	v_add_co_u32_e32 v34, vcc, 0x4000, v32
	s_add_u32 s18, s18, s0
	s_nop 0
	v_addc_co_u32_e32 v35, vcc, 0, v33, vcc
	v_add_co_u32_e32 v32, vcc, 0x6000, v32
	s_addc_u32 s19, s19, s1
	s_lshl_b64 s[46:47], s[14:15], 13
	v_addc_co_u32_e32 v33, vcc, 0, v33, vcc
	s_lshl_b64 s[18:19], s[18:19], 7
	flat_load_dwordx4 v[112:115], v[34:35]
	flat_load_dwordx4 v[116:119], v[32:33]
	v_lshl_add_u64 v[32:33], v[144:145], 0, s[46:47]
	v_lshl_add_u64 v[34:35], v[146:147], 0, s[18:19]
	flat_load_dwordx4 v[120:123], v[32:33]
	flat_load_dwordx4 v[124:127], v[34:35]
	s_and_saveexec_b64 s[18:19], s[40:41]
	s_cbranch_execz .LBB0_716
	s_lshl_b64 s[12:13], s[14:15], 10
	v_lshl_add_u64 v[32:33], v[148:149], 0, s[12:13]
	flat_load_dwordx4 v[108:111], v[32:33]
